# S5 prompt item: trailing workgroup barrier taken only when another item follows (the sample items that follow use no LDS), so the staggered waves do not re-synchronise
# baseline (speedup 1.0000x reference)
; __device__ __forceinline__ float gelu_tanh(float x) { const float u = 1.5957691216057308f * (x + 0.044715f * x * x * x); return x * sigmoid_f(u); }
; #define LAS __attribute__((address_space(3)))
; __device__ __forceinline__ unsigned pk2(float lo, float hi) { unsigned r; asm("v_cvt_pk_bf16_f32 %0, %1, %2" : "=v"(r) : "v"(lo), "v"(hi)); return r; }
; __device__ __forceinline__ float bflo(unsigned w) { return __uint_as_float(w << 16); }
; __device__ __forceinline__ float bfhi(unsigned w) { return __uint_as_float(w & 0xffff0000u); }
; __device__ __forceinline__ void s5_prompt_item_mfma(LAS unsigned char* lds, int tid0, int lane0, int wave, int n, int g, const bf16* USg, const bf16* FTg, const bf16* WTg, const bf16* GTg, ...
;     ...
; #pragma unroll
;         for (int kk = 0; kk < 4; ++kk)
; #pragma unroll
;             for (int cb = 0; cb < 4; ++cb) acc[cb] = __builtin_amdgcn_mfma_f32_16x16x32_bf16(ga[j][kk], hbv[kk][cb], acc[cb], 0, 0, 0);
; #pragma unroll
;         for (int cb = 0; cb < 4; ++cb) { const int tok = (16 * cb + fr) * S5T + tau;
;             const v2u uu = *(const LAS v2u*)(lds + U_OFF + (16 * cb + fr) * 1056 + tau * 32 + 8 * fq);
;             const float y0 = gelu_tanh(acc[cb][0] + dk[0] * bflo(uu.x)), y1 = gelu_tanh(acc[cb][1] + dk[1] * bfhi(uu.x)), y2 = gelu_tanh(acc[cb][2] + dk[2] * bflo(uu.y)), y3 = gelu_tanh(acc[cb][3] + dk[3] * bfhi(uu.y));
;             v2u o; o.x = pk2(y0, y1); o.y = pk2(y2, y3);
;             *(v2u*)(YS + ((size_t)n * SEQ + tok) * SSMW + g * 16 + 4 * fq) = o; }
.LBB0_847:
	s_nop 0
	v_mfma_f32_16x16x32_bf16 v[84:87], v[16:19], v[84:87], v[120:123]
	v_add3_u32 v2, v178, s26, v2
	s_add_i32 s64, s64, s67
	s_cmpk_gt_i32 s64, 0xff
	v_mfma_f32_16x16x32_bf16 v[76:79], v[12:15], v[76:79], v[84:87]
	v_mfma_f32_16x16x32_bf16 v[76:79], v[8:11], v[80:83], v[76:79]
	s_nop 2
	ds_read2st64_b64 v[84:87], v2 offset1:33
	v_add_u32_e32 v80, s24, v179
	s_waitcnt lgkmcnt(0)
	v_lshlrev_b32_e32 v81, 16, v84
	v_mfma_f32_16x16x32_bf16 v[72:75], v[4:7], v[72:75], v[76:79]
	v_and_b32_e32 v82, 0xffff0000, v84
	v_mfma_f32_16x16x32_bf16 v[68:71], v[16:19], v[68:71], v[116:119]
	v_mfma_f32_16x16x32_bf16 v[64:67], v[16:19], v[64:67], v[112:115]
	s_nop 4
	v_fma_f32 v72, v20, v81, v72
	v_fma_f32 v73, v21, v82, v73
	v_mul_f32_e32 v76, 0x3d372713, v72
	v_mfma_f32_16x16x32_bf16 v[16:19], v[16:19], v[60:63], v[108:111]
	v_lshlrev_b32_e32 v62, 16, v85
	v_fma_f32 v62, v22, v62, v74
	v_mul_f32_e32 v63, 0x3d372713, v62
	v_mfma_f32_16x16x32_bf16 v[56:59], v[12:15], v[56:59], v[68:71]
	v_mul_f32_e32 v77, 0x3d372713, v73
	v_mul_f32_e32 v63, v62, v63
	v_mul_f32_e32 v76, v72, v76
	v_mfma_f32_16x16x32_bf16 v[48:51], v[12:15], v[48:51], v[64:67]
	v_mul_f32_e32 v77, v73, v77
	v_fma_f32 v63, v62, v63, v62
	v_fma_f32 v76, v72, v76, v72
	v_mfma_f32_16x16x32_bf16 v[12:15], v[12:15], v[44:47], v[16:19]
	v_and_b32_e32 v45, 0xffff0000, v85
	v_fmac_f32_e32 v75, v23, v45
	v_mul_f32_e32 v45, 0x3d372713, v75
	v_mul_f32_e32 v45, v75, v45
	v_fma_f32 v77, v73, v77, v73
	v_mul_f32_e32 v16, 0x3fcc422a, v63
	v_fma_f32 v45, v75, v45, v75
	v_mul_f32_e32 v76, 0x3fcc422a, v76
	v_mul_f32_e32 v77, 0x3fcc422a, v77
	v_mul_f32_e32 v16, 0xbfb8aa3b, v16
	v_mul_f32_e32 v45, 0x3fcc422a, v45
	v_mul_f32_e32 v76, 0xbfb8aa3b, v76
	v_mul_f32_e32 v77, 0xbfb8aa3b, v77
	v_exp_f32_e32 v44, v16
	v_mfma_f32_16x16x32_bf16 v[16:19], v[8:11], v[52:55], v[56:59]
	v_exp_f32_e32 v76, v76
	v_exp_f32_e32 v77, v77
	v_ashrrev_i32_e32 v81, 31, v80
	v_mfma_f32_16x16x32_bf16 v[40:43], v[8:11], v[40:43], v[48:51]
	v_add_f32_e32 v76, 1.0, v76
	v_add_f32_e32 v61, 1.0, v77
	v_rcp_f32_e32 v60, v76
	v_mfma_f32_16x16x32_bf16 v[8:11], v[8:11], v[36:39], v[12:15]
	v_add_f32_e32 v37, 1.0, v44
	v_rcp_f32_e32 v61, v61
	v_mul_f32_e32 v60, v72, v60
	v_mul_f32_e32 v12, 0xbfb8aa3b, v45
	v_exp_f32_e32 v36, v12
	v_mfma_f32_16x16x32_bf16 v[12:15], v[4:7], v[32:35], v[16:19]
	v_rcp_f32_e32 v32, v37
	s_nop 1
	v_add_f32_e32 v16, 1.0, v36
	v_rcp_f32_e32 v33, v16
	v_mfma_f32_16x16x32_bf16 v[16:19], v[4:7], v[28:31], v[40:43]
	v_mul_f32_e32 v28, v73, v61
	v_mul_f32_e32 v29, v62, v32
	v_mul_f32_e32 v30, v75, v33
	v_mfma_f32_16x16x32_bf16 v[4:7], v[4:7], v[24:27], v[8:11]
	v_cvt_pk_bf16_f32 v8, v60, v28
	v_cvt_pk_bf16_f32 v9, v29, v30
	v_and_b32_e32 v24, 0xffff0000, v87
	v_fmac_f32_e32 v15, v23, v24
	v_mul_f32_e32 v24, 0x3d372713, v15
	v_lshl_add_u64 v[10:11], s[8:9], 0, v[80:81]
	v_lshlrev_b64 v[10:11], 10, v[10:11]
	v_lshl_add_u64 v[10:11], v[176:177], 0, v[10:11]
	global_store_dwordx2 v[10:11], v[8:9], off
	v_and_b32_e32 v10, 0xffff0000, v86
	v_lshlrev_b32_e32 v8, 16, v86
	v_fma_f32 v10, v21, v10, v13
	v_lshlrev_b32_e32 v13, 16, v87
	v_fma_f32 v8, v20, v8, v12
	v_fma_f32 v13, v22, v13, v14
	v_mul_f32_e32 v9, 0x3d372713, v8
	v_mul_f32_e32 v11, 0x3d372713, v10
	v_mul_f32_e32 v14, 0x3d372713, v13
	v_mul_f32_e32 v9, v8, v9
	v_mul_f32_e32 v11, v10, v11
	v_mul_f32_e32 v14, v13, v14
	v_mul_f32_e32 v24, v15, v24
	v_fma_f32 v9, v8, v9, v8
	v_fma_f32 v11, v10, v11, v10
	v_fma_f32 v14, v13, v14, v13
	v_fma_f32 v24, v15, v24, v15
	v_mul_f32_e32 v9, 0x3fcc422a, v9
	v_mul_f32_e32 v11, 0x3fcc422a, v11
	v_mul_f32_e32 v14, 0x3fcc422a, v14
	v_mul_f32_e32 v24, 0x3fcc422a, v24
	v_mul_f32_e32 v9, 0xbfb8aa3b, v9
	v_mul_f32_e32 v11, 0xbfb8aa3b, v11
	v_mul_f32_e32 v14, 0xbfb8aa3b, v14
	v_mul_f32_e32 v24, 0xbfb8aa3b, v24
	v_exp_f32_e32 v9, v9
	v_exp_f32_e32 v11, v11
	v_exp_f32_e32 v14, v14
	v_exp_f32_e32 v24, v24
	v_add_f32_e32 v9, 1.0, v9
	v_add_f32_e32 v11, 1.0, v11
	v_add_f32_e32 v14, 1.0, v14
	v_add_f32_e32 v24, 1.0, v24
	v_rcp_f32_e32 v9, v9
	v_rcp_f32_e32 v11, v11
	v_rcp_f32_e32 v14, v14
	v_rcp_f32_e32 v24, v24
	v_mul_f32_e32 v8, v8, v9
	v_mul_f32_e32 v9, v10, v11
	v_mul_f32_e32 v10, v13, v14
	v_mul_f32_e32 v11, v15, v24
	v_cvt_pk_bf16_f32 v14, v8, v9
	v_cvt_pk_bf16_f32 v15, v10, v11
	ds_read2st64_b64 v[8:11], v2 offset0:66 offset1:99
	v_add_u32_e32 v12, s24, v180
	v_ashrrev_i32_e32 v13, 31, v12
	v_lshl_add_u64 v[12:13], s[8:9], 0, v[12:13]
	v_lshlrev_b64 v[12:13], 10, v[12:13]
	v_lshl_add_u64 v[12:13], v[176:177], 0, v[12:13]
	s_waitcnt lgkmcnt(0)
; __device__ __forceinline__ float gelu_tanh(float x) { const float u = 1.5957691216057308f * (x + 0.044715f * x * x * x); return x * sigmoid_f(u); }
; #define LAS __attribute__((address_space(3)))
; __device__ __forceinline__ unsigned pk2(float lo, float hi) { unsigned r; asm("v_cvt_pk_bf16_f32 %0, %1, %2" : "=v"(r) : "v"(lo), "v"(hi)); return r; }
; __device__ __forceinline__ float bflo(unsigned w) { return __uint_as_float(w << 16); }
; __device__ __forceinline__ float bfhi(unsigned w) { return __uint_as_float(w & 0xffff0000u); }
; __device__ __forceinline__ void s5_prompt_item_mfma(LAS unsigned char* lds, int tid0, int lane0, int wave, int n, int g, const bf16* USg, const bf16* FTg, const bf16* WTg, const bf16* GTg, ...
;     ...
;         for (int cb = 0; cb < 4; ++cb) { const int tok = (16 * cb + fr) * S5T + tau;
;             const v2u uu = *(const LAS v2u*)(lds + U_OFF + (16 * cb + fr) * 1056 + tau * 32 + 8 * fq);
;             const float y0 = gelu_tanh(acc[cb][0] + dk[0] * bflo(uu.x)), y1 = gelu_tanh(acc[cb][1] + dk[1] * bfhi(uu.x)), y2 = gelu_tanh(acc[cb][2] + dk[2] * bflo(uu.y)), y3 = gelu_tanh(acc[cb][3] + dk[3] * bfhi(uu.y));
;             v2u o; o.x = pk2(y0, y1); o.y = pk2(y2, y3);
;             *(v2u*)(YS + ((size_t)n * SEQ + tok) * SSMW + g * 16 + 4 * fq) = o; }
;     }
;     __syncthreads();
	v_lshlrev_b32_e32 v2, 16, v8
	v_and_b32_e32 v8, 0xffff0000, v8
	global_store_dwordx2 v[12:13], v[14:15], off
	v_fma_f32 v2, v20, v2, v16
	v_fma_f32 v13, v21, v8, v17
	v_mul_f32_e32 v12, 0x3d372713, v2
	v_mul_f32_e32 v8, 0x3d372713, v13
	v_mul_f32_e32 v12, v2, v12
	v_mul_f32_e32 v8, v13, v8
	v_lshlrev_b32_e32 v15, 16, v9
	v_and_b32_e32 v9, 0xffff0000, v9
	v_fma_f32 v12, v2, v12, v2
	v_fma_f32 v8, v13, v8, v13
	v_fma_f32 v15, v22, v15, v18
	v_fmac_f32_e32 v19, v23, v9
	v_mul_f32_e32 v12, 0x3fcc422a, v12
	v_mul_f32_e32 v8, 0x3fcc422a, v8
	v_mul_f32_e32 v16, 0x3d372713, v15
	v_mul_f32_e32 v9, 0x3d372713, v19
	v_mul_f32_e32 v12, 0xbfb8aa3b, v12
	v_mul_f32_e32 v8, 0xbfb8aa3b, v8
	v_mul_f32_e32 v16, v15, v16
	v_mul_f32_e32 v9, v19, v9
	v_exp_f32_e32 v12, v12
	v_exp_f32_e32 v14, v8
	v_fma_f32 v16, v15, v16, v15
	v_fma_f32 v9, v19, v9, v19
	v_mul_f32_e32 v16, 0x3fcc422a, v16
	v_mul_f32_e32 v9, 0x3fcc422a, v9
	v_mul_f32_e32 v16, 0xbfb8aa3b, v16
	v_mul_f32_e32 v9, 0xbfb8aa3b, v9
	v_exp_f32_e32 v16, v16
	v_exp_f32_e32 v9, v9
	v_add_f32_e32 v12, 1.0, v12
	v_add_f32_e32 v14, 1.0, v14
	v_rcp_f32_e32 v12, v12
	v_rcp_f32_e32 v14, v14
	v_add_f32_e32 v16, 1.0, v16
	v_add_f32_e32 v9, 1.0, v9
	v_rcp_f32_e32 v16, v16
	v_rcp_f32_e32 v9, v9
	v_mul_f32_e32 v2, v2, v12
	v_mul_f32_e32 v12, v13, v14
	v_cvt_pk_bf16_f32 v12, v2, v12
	v_lshlrev_b32_e32 v2, 16, v10
	v_fma_f32 v2, v20, v2, v4
	v_add_u32_e32 v8, s24, v181
	v_mul_f32_e32 v13, v15, v16
	v_mul_f32_e32 v9, v19, v9
	v_mul_f32_e32 v4, 0x3d372713, v2
	v_cvt_pk_bf16_f32 v13, v13, v9
	v_ashrrev_i32_e32 v9, 31, v8
	v_mul_f32_e32 v4, v2, v4
	v_lshl_add_u64 v[8:9], s[8:9], 0, v[8:9]
	v_fma_f32 v4, v2, v4, v2
	v_lshlrev_b64 v[8:9], 10, v[8:9]
	v_mul_f32_e32 v4, 0x3fcc422a, v4
	v_lshl_add_u64 v[8:9], v[176:177], 0, v[8:9]
	v_mul_f32_e32 v4, 0xbfb8aa3b, v4
	global_store_dwordx2 v[8:9], v[12:13], off
	v_exp_f32_e32 v8, v4
	v_and_b32_e32 v4, 0xffff0000, v10
	v_fma_f32 v5, v21, v4, v5
	v_lshlrev_b32_e32 v10, 16, v11
	v_mul_f32_e32 v4, 0x3d372713, v5
	v_fma_f32 v6, v22, v10, v6
	v_mul_f32_e32 v4, v5, v4
	v_mul_f32_e32 v10, 0x3d372713, v6
	v_fma_f32 v4, v5, v4, v5
	v_mul_f32_e32 v10, v6, v10
	v_and_b32_e32 v11, 0xffff0000, v11
	v_mul_f32_e32 v4, 0x3fcc422a, v4
	v_fma_f32 v10, v6, v10, v6
	v_fmac_f32_e32 v7, v23, v11
	v_mul_f32_e32 v4, 0xbfb8aa3b, v4
	v_mul_f32_e32 v10, 0x3fcc422a, v10
	v_mul_f32_e32 v11, 0x3d372713, v7
	v_exp_f32_e32 v9, v4
	v_mul_f32_e32 v10, 0xbfb8aa3b, v10
	v_mul_f32_e32 v11, v7, v11
	v_exp_f32_e32 v10, v10
	v_fma_f32 v11, v7, v11, v7
	v_mul_f32_e32 v11, 0x3fcc422a, v11
	v_mul_f32_e32 v11, 0xbfb8aa3b, v11
	v_add_f32_e32 v9, 1.0, v9
	v_exp_f32_e32 v11, v11
	v_add_f32_e32 v8, 1.0, v8
	v_rcp_f32_e32 v9, v9
	v_add_f32_e32 v10, 1.0, v10
	v_rcp_f32_e32 v8, v8
	v_rcp_f32_e32 v10, v10
	v_add_f32_e32 v11, 1.0, v11
	v_add_u32_e32 v4, s24, v182
	v_rcp_f32_e32 v11, v11
	v_mul_f32_e32 v5, v5, v9
	v_mul_f32_e32 v2, v2, v8
	v_mul_f32_e32 v8, v6, v10
	v_cvt_pk_bf16_f32 v6, v2, v5
	v_ashrrev_i32_e32 v5, 31, v4
	v_lshl_add_u64 v[4:5], s[8:9], 0, v[4:5]
	v_lshlrev_b64 v[4:5], 10, v[4:5]
	v_mul_f32_e32 v7, v7, v11
	v_lshl_add_u64 v[4:5], v[176:177], 0, v[4:5]
	v_cvt_pk_bf16_f32 v7, v8, v7
	global_store_dwordx2 v[4:5], v[6:7], off
	s_cbranch_scc1 .LBB0_890
	s_barrier
